# P4: SSQ row-partial loads for the next tile issued during the current epilogue (one tile ahead) so the K-loop's in-order vmcnt waits never stall on them
# baseline (speedup 1.0000x reference)
; #define PG8_STAGE(bufoff, gbase, voff) do { _Pragma("unroll") for (int _i = 0; _i < 2; ++_i) \
;         __builtin_amdgcn_global_load_lds((const unsigned*)((const char*)(gbase) + (voff)[_i]), (PG8_LAS unsigned*)(lds + (bufoff) + ldsw + _i * 8192), 16, 0, 0); } while (0)
; #define PG8_WAIT_V(n) asm volatile("s_waitcnt vmcnt(" #n ")" ::: "memory")
; #define PG8_BAR __builtin_amdgcn_s_barrier()
; template <class Epi, class Sched, bool ALIGN_EPI = false, bool SP2 = false>
; __device__ __forceinline__ void gemm_phase(PG8_LAS unsigned char* lds, const Gemm g, const Sched& S, const Epi& E) {
;     ...
;     for (int i = 0; i < 2; ++i) { int R, C; stage_rc(tid * 16 + i * 8192, R, C); const int Rb = Epi::PERM ? ((R & ~31) + perm32(R & 31)) : R;
;         voffA[i] = (unsigned)(R * K + C) * 2u; voffB[i] = (unsigned)(Rb * K + C) * 2u; }
;     const size_t kstep = (size_t)(BK * 2);
;     const size_t hstep = (size_t)HALF * K * 2;
;     const size_t tstep = 2 * hstep;
;     const unsigned ldsw = (unsigned)wid * 1024u;
;     const int aoff = lds_byte(wr * 64 + fr, fq * 8), boff = lds_byte(wc * 32 + fr, fq * 8);
;     ...
;         PG8_STAGE(PG8_SB(0, 0), cB, voffB); PG8_STAGE(PG8_SB(0, 1), cB + hstep, voffB); PG8_STAGE(PG8_SA(0, 0), cA, voffA); PG8_STAGE(PG8_SA(0, 1), cA + hstep, voffA);
;         if (wr == 1) PG8_BAR;
;         PG8_WAIT_V(2); PG8_BAR;
;         PG8_STAGE(PG8_SB(1, 0), cB + kstep, voffB); PG8_STAGE(PG8_SA(1, 0), cA + kstep, voffA); PG8_STAGE(PG8_SB(1, 1), cB + hstep + kstep, voffB);
;         PG8_WAIT_V(6); PG8_BAR;
.LBB0_854:
	s_lshl_b32 s12, s12, 5
	s_and_b32 s17, s12, 0x60
	s_mov_b64 s[12:13], 0x80
	s_add_i32 m0, s38, 0x18000
	v_lshl_add_u64 v[6:7], v[6:7], 0, s[12:13]
	s_lshl_b32 s16, s8, 13
	s_lshl_b32 s18, s17, 7
	s_waitcnt vmcnt(2)
	s_barrier
	global_load_lds_dwordx4 v[6:7], off
	v_lshl_add_u64 v[4:5], v[4:5], 0, s[12:13]
	s_add_i32 m0, s38, 0x1a000
	s_add_i32 s42, s38, 0x8000
	s_add_i32 s43, s38, 0xa000
	global_load_lds_dwordx4 v[4:5], off
	v_lshl_add_u64 v[0:1], v[0:1], 0, s[12:13]
	s_mov_b32 m0, s42
	s_add_u32 s14, s28, 0x40080
	global_load_lds_dwordx4 v[0:1], off
	v_lshl_add_u64 v[0:1], v[2:3], 0, s[12:13]
	s_mov_b32 m0, s43
	s_addc_u32 s15, s29, 0
	global_load_lds_dwordx4 v[0:1], off
	s_add_i32 m0, s38, 0x1c000
	v_lshl_add_u64 v[0:1], s[14:15], 0, v[132:133]
	global_load_lds_dwordx4 v[0:1], off
	v_lshl_add_u64 v[0:1], s[14:15], 0, v[128:129]
	s_add_i32 m0, s38, 0x1e000
	s_cmpk_lt_u32 s7, 0x100
	global_load_lds_dwordx4 v[0:1], off
	v_lshrrev_b32_e32 v0, 1, v10
	v_and_b32_e32 v0, 24, v0
	v_and_b32_e32 v1, 15, v10
	v_lshlrev_b32_e32 v2, 1, v0
	v_lshl_or_b32 v150, s8, 6, v1
	v_lshl_or_b32 v1, v1, 6, v2
	v_lshlrev_b32_e32 v2, 2, v10
	v_and_b32_e32 v2, 32, v2
	v_bitop3_b32 v3, v1, s16, v2 bitop3:0xde
	v_bitop3_b32 v151, v1, s18, v2 bitop3:0xde
	v_lshlrev_b32_e32 v1, 14, v13
	v_and_b32_e32 v1, 0xffff8000, v1
	v_lshl_add_u32 v1, v12, 11, v1
	v_and_b32_e32 v2, 1, v13
	v_lshl_or_b32 v1, v2, 6, v1
	v_lshl_add_u32 v138, v14, 1, v1
	v_lshlrev_b32_e32 v1, 14, v8
	v_and_b32_e32 v1, 0xffff8000, v1
	s_waitcnt vmcnt(6)
	v_lshl_add_u32 v1, v9, 11, v1
	v_and_b32_e32 v2, 1, v8
	s_cselect_b64 s[14:15], -1, 0
	v_lshl_or_b32 v1, v2, 6, v1
	s_add_i32 s45, 0, 0x10000
	s_add_i32 s46, 0, 0x14000
	s_sext_i32_i16 s25, s6
	s_ashr_i32 s44, s3, 31
	v_mov_b32_e32 v139, v137
	v_lshl_add_u32 v140, v11, 1, v1
	v_mov_b32_e32 v141, v137
	v_mov_b64_e32 v[142:143], 0x1658
	v_mov_b64_e32 v[144:145], 0x1657
	v_add_u32_e32 v152, s45, v151
	v_add_u32_e32 v153, s46, v151
	v_add_u32_e32 v154, 0, v3
	v_mov_b32_e32 v155, 0x358637bd
	s_mov_b32 s47, 0x800000
	s_movk_i32 s48, 0x1600
	s_lshl_b32 s8, s17, 1
	v_lshlrev_b32_e32 v136, 1, v0
	s_mov_b32 s49, s9
	v_and_b32_e32 v246, 0xff, v182
	v_lshlrev_b32_e32 v247, 2, v246
	v_add_u32_e32 v247, 0x20000, v247
	v_lshlrev_b32_e32 v246, 6, v246
	s_waitcnt vmcnt(0)
	s_lshl_b32 s59, s24, 14
	v_add_u32_e32 v248, s59, v246
	global_load_dwordx4 v[230:233], v248, s[0:1]
	global_load_dwordx4 v[234:237], v248, s[0:1] offset:16
	global_load_dwordx4 v[238:241], v248, s[0:1] offset:32
	global_load_dwordx4 v[242:245], v248, s[0:1] offset:48
	s_barrier
	s_branch .LBB0_857

; #define PG8_STAGE(bufoff, gbase, voff) do { _Pragma("unroll") for (int _i = 0; _i < 2; ++_i) \
;         __builtin_amdgcn_global_load_lds((const unsigned*)((const char*)(gbase) + (voff)[_i]), (PG8_LAS unsigned*)(lds + (bufoff) + ldsw + _i * 8192), 16, 0, 0); } while (0)
; #define PG8_LDA(dst, b, h) do { _Pragma("unroll") for (int m = 0; m < 4; ++m) _Pragma("unroll") for (int k = 0; k < 2; ++k) dst[m][k] = *(const PG8_LAS bf16x8*)(lds + PG8_SA(b, h) + aoff + m * 2048 + k * 1024); } while (0)
; #define PG8_LDB(dst, b, h) do { _Pragma("unroll") for (int n = 0; n < 2; ++n) _Pragma("unroll") for (int k = 0; k < 2; ++k) dst[n][k] = *(const PG8_LAS bf16x8*)(lds + PG8_SB(b, h) + boff + n * 2048 + k * 1024); } while (0)
; #define PG8_WAIT_V(n) asm volatile("s_waitcnt vmcnt(" #n ")" ::: "memory")
; #define PG8_WAIT_L(n) asm volatile("s_waitcnt lgkmcnt(" #n ")" ::: "memory")
; #define PG8_BAR __builtin_amdgcn_s_barrier()
; #define PG8_SCHED __builtin_amdgcn_sched_barrier(0)
; template <class Epi, class Sched, bool ALIGN_EPI = false, bool SP2 = false>
; __device__ __forceinline__ void gemm_phase(PG8_LAS unsigned char* lds, const Gemm g, const Sched& S, const Epi& E) {
;     ...
;         const char* nA = has_next ? (const char*)g.A + (size_t)nxt.pm * tstep : cA; const char* nB = has_next ? (const char*)g.Bt + (size_t)nxt.pn * tstep : cB;
;         for (int t = 0; t < nt; t += 2) {
;             const bool last = (t == nt - 2);
;             const char* a1 = cA + (size_t)(t + 1) * kstep;
;             const char* a2 = last ? nA : cA + (size_t)(t + 2) * kstep; const char* b2 = last ? nB : cB + (size_t)(t + 2) * kstep;
;             const char* a3 = a2 + kstep; const char* b3 = b2 + kstep;
;             if (last && has_next) S.a_ready(nxt);
;             if constexpr (SP2) {
;             PG8_LDB(B0, 0, 0); PG8_LDB(B1, 0, 1); PG8_SCHED; PG8_LDA(At, 0, 0); PG8_STAGE(PG8_SA(1, 1), a1 + hstep, voffA);
;             PG8_WAIT_V(8); PG8_WAIT_L(0); PG8_BAR; PG8_MMA(0, 0, At, B0); PG8_MMA(0, 1, At, B1); PG8_BAR; PG8_SCHED;
;             PG8_LDA(At, 0, 1); PG8_STAGE(PG8_SB(0, 0), b2, voffB); PG8_STAGE(PG8_SB(0, 1), b2 + hstep, voffB); PG8_STAGE(PG8_SA(0, 0), a2, voffA);
;             PG8_WAIT_V(8); PG8_WAIT_L(0); PG8_BAR; PG8_MMA(1, 0, At, B0); PG8_MMA(1, 1, At, B1); PG8_BAR; PG8_SCHED;
.LBB0_859:
	s_ashr_i32 s19, s18, 31
	s_lshl_b64 s[20:21], s[18:19], 19
	s_add_u32 s20, s50, s20
	s_addc_u32 s21, s51, s21
	s_and_b64 s[22:23], s[6:7], exec
	s_cselect_b32 s19, s21, s27
	s_cselect_b32 s54, s20, s26
	s_ashr_i32 s17, s16, 31
	s_lshl_b64 s[22:23], s[16:17], 19
	s_add_u32 s22, s33, s22
	s_addc_u32 s23, s34, s23
	s_and_b64 s[30:31], s[6:7], exec
	s_cselect_b32 s17, s23, s29
	s_cselect_b32 s55, s22, s28
	s_add_u32 s26, s26, 0x40080
	s_addc_u32 s27, s27, 0
	s_add_u32 s56, s28, 0x100
	s_addc_u32 s57, s29, 0
	s_mov_b32 s58, -2
	ds_read_b128 v[146:149], v152
	ds_read_b128 v[156:159], v152 offset:1024
	ds_read_b128 v[160:163], v152 offset:2048
	ds_read_b128 v[164:167], v152 offset:3072
	ds_read_b128 v[168:171], v153
	ds_read_b128 v[172:175], v153 offset:1024
	ds_read_b128 v[176:179], v153 offset:2048
	ds_read_b128 v[186:189], v153 offset:3072
	s_add_u32 s28, s26, 0xfffc0080
	s_addc_u32 s29, s27, -1
	s_cmp_eq_u32 s58, 12
	s_cselect_b32 s31, s19, s29
	s_cselect_b32 s30, s54, s28
	s_cselect_b32 s29, s17, s57
	s_cselect_b32 s28, s55, s56
	v_lshl_add_u64 v[180:181], s[26:27], 0, v[138:139]
	s_add_i32 m0, s38, 0xc000
	ds_read_b128 v[190:193], v154
	ds_read_b128 v[194:197], v154 offset:1024
	ds_read_b128 v[198:201], v154 offset:2048
	ds_read_b128 v[202:205], v154 offset:3072
	ds_read_b128 v[206:209], v154 offset:4096
	ds_read_b128 v[210:213], v154 offset:5120
	ds_read_b128 v[214:217], v154 offset:6144
	ds_read_b128 v[218:221], v154 offset:7168
	global_load_lds_dwordx4 v[180:181], off
	v_lshl_add_u64 v[180:181], s[26:27], 0, v[140:141]
	s_add_i32 m0, s38, 0xe000
	s_nop 0
	global_load_lds_dwordx4 v[180:181], off
	s_waitcnt vmcnt(20)
	s_waitcnt lgkmcnt(0)
	s_barrier
	s_setprio 1
	s_waitcnt lgkmcnt(0)
	v_mfma_f32_16x16x32_bf16 v[124:127], v[146:149], v[190:193], 0
	v_mfma_f32_16x16x32_bf16 v[120:123], v[160:163], v[190:193], 0
	v_mfma_f32_16x16x32_bf16 v[108:111], v[146:149], v[198:201], 0
	v_mfma_f32_16x16x32_bf16 v[104:107], v[160:163], v[198:201], 0
	v_mfma_f32_16x16x32_bf16 v[92:95], v[146:149], v[206:209], 0
	v_mfma_f32_16x16x32_bf16 v[88:91], v[160:163], v[206:209], 0
	v_mfma_f32_16x16x32_bf16 v[76:79], v[146:149], v[214:217], 0
	v_mfma_f32_16x16x32_bf16 v[72:75], v[160:163], v[214:217], 0
	v_mfma_f32_16x16x32_bf16 v[124:127], v[156:159], v[194:197], v[124:127]
	v_mfma_f32_16x16x32_bf16 v[120:123], v[164:167], v[194:197], v[120:123]
	v_mfma_f32_16x16x32_bf16 v[108:111], v[156:159], v[202:205], v[108:111]
	v_mfma_f32_16x16x32_bf16 v[104:107], v[164:167], v[202:205], v[104:107]
	v_mfma_f32_16x16x32_bf16 v[92:95], v[156:159], v[210:213], v[92:95]
	v_mfma_f32_16x16x32_bf16 v[88:91], v[164:167], v[210:213], v[88:91]
	v_mfma_f32_16x16x32_bf16 v[76:79], v[156:159], v[218:221], v[76:79]
	v_mfma_f32_16x16x32_bf16 v[72:75], v[164:167], v[218:221], v[72:75]
	s_setprio 0
	s_setprio 1
	v_mfma_f32_16x16x32_bf16 v[116:119], v[168:171], v[190:193], 0
	v_mfma_f32_16x16x32_bf16 v[112:115], v[176:179], v[190:193], 0
	v_mfma_f32_16x16x32_bf16 v[100:103], v[168:171], v[198:201], 0
	v_mfma_f32_16x16x32_bf16 v[96:99], v[176:179], v[198:201], 0
	v_mfma_f32_16x16x32_bf16 v[84:87], v[168:171], v[206:209], 0
	v_mfma_f32_16x16x32_bf16 v[80:83], v[176:179], v[206:209], 0
	v_mfma_f32_16x16x32_bf16 v[68:71], v[168:171], v[214:217], 0
	v_mfma_f32_16x16x32_bf16 v[64:67], v[176:179], v[214:217], 0
	v_mfma_f32_16x16x32_bf16 v[116:119], v[172:175], v[194:197], v[116:119]
	v_mfma_f32_16x16x32_bf16 v[112:115], v[186:189], v[194:197], v[112:115]
	v_mfma_f32_16x16x32_bf16 v[100:103], v[172:175], v[202:205], v[100:103]
	v_mfma_f32_16x16x32_bf16 v[96:99], v[186:189], v[202:205], v[96:99]
	v_mfma_f32_16x16x32_bf16 v[84:87], v[172:175], v[210:213], v[84:87]
	v_mfma_f32_16x16x32_bf16 v[80:83], v[186:189], v[210:213], v[80:83]
	v_mfma_f32_16x16x32_bf16 v[68:71], v[172:175], v[218:221], v[68:71]
	v_mfma_f32_16x16x32_bf16 v[64:67], v[186:189], v[218:221], v[64:67]
	s_setprio 0
	s_barrier
	s_add_i32 s59, s45, s35
	v_lshl_add_u64 v[180:181], s[28:29], 0, v[132:133]
	s_mov_b32 m0, s59
	ds_read_b128 v[190:193], v154 offset:16384
	ds_read_b128 v[194:197], v154 offset:17408
	ds_read_b128 v[198:201], v154 offset:18432
	ds_read_b128 v[202:205], v154 offset:19456
	ds_read_b128 v[206:209], v154 offset:20480
	ds_read_b128 v[210:213], v154 offset:21504
	ds_read_b128 v[214:217], v154 offset:22528
	ds_read_b128 v[218:221], v154 offset:23552
	global_load_lds_dwordx4 v[180:181], off
	s_add_i32 m0, s59, 0x2000
	s_add_u32 s60, s28, 0x40000
	v_lshl_add_u64 v[222:223], s[28:29], 0, v[128:129]
	s_addc_u32 s61, s29, 0
	s_add_i32 s59, s46, s35
	global_load_lds_dwordx4 v[222:223], off
	v_lshl_add_u64 v[224:225], s[60:61], 0, v[132:133]
	s_mov_b32 m0, s59
	v_lshl_add_u64 v[226:227], s[30:31], 0, v[130:131]
	global_load_lds_dwordx4 v[224:225], off
	v_lshl_add_u64 v[224:225], s[60:61], 0, v[128:129]
	s_add_i32 m0, s59, 0x2000
	s_nop 0
	global_load_lds_dwordx4 v[224:225], off
	v_lshl_add_u64 v[224:225], s[30:31], 0, v[134:135]
	s_mov_b32 m0, s38
	s_nop 0
	global_load_lds_dwordx4 v[224:225], off
	s_mov_b32 m0, s39
	s_nop 0
	global_load_lds_dwordx4 v[226:227], off
	s_waitcnt vmcnt(20)
	s_waitcnt lgkmcnt(0)
	s_barrier
; #define PG8_STAGE(bufoff, gbase, voff) do { _Pragma("unroll") for (int _i = 0; _i < 2; ++_i) \
;         __builtin_amdgcn_global_load_lds((const unsigned*)((const char*)(gbase) + (voff)[_i]), (PG8_LAS unsigned*)(lds + (bufoff) + ldsw + _i * 8192), 16, 0, 0); } while (0)
; #define PG8_LDA(dst, b, h) do { _Pragma("unroll") for (int m = 0; m < 4; ++m) _Pragma("unroll") for (int k = 0; k < 2; ++k) dst[m][k] = *(const PG8_LAS bf16x8*)(lds + PG8_SA(b, h) + aoff + m * 2048 + k * 1024); } while (0)
; #define PG8_LDB(dst, b, h) do { _Pragma("unroll") for (int n = 0; n < 2; ++n) _Pragma("unroll") for (int k = 0; k < 2; ++k) dst[n][k] = *(const PG8_LAS bf16x8*)(lds + PG8_SB(b, h) + boff + n * 2048 + k * 1024); } while (0)
; #define PG8_MMA(ai, bj, At, Bt) do { __builtin_amdgcn_s_setprio(1); _Pragma("unroll") for (int m = 0; m < 4; ++m) _Pragma("unroll") for (int n = 0; n < 2; ++n) _Pragma("unroll") for (int k = 0; k < 2; ++k) \
;         acc[ai][bj][m][n] = __builtin_amdgcn_mfma_f32_16x16x32_bf16(Bt[n][k], At[m][k], acc[ai][bj][m][n], 0, 0, 0); __builtin_amdgcn_s_setprio(0); } while (0)
; #define PG8_WAIT_V(n) asm volatile("s_waitcnt vmcnt(" #n ")" ::: "memory")
; #define PG8_WAIT_L(n) asm volatile("s_waitcnt lgkmcnt(" #n ")" ::: "memory")
; #define PG8_BAR __builtin_amdgcn_s_barrier()
; #define PG8_SCHED __builtin_amdgcn_sched_barrier(0)
; template <class Epi, class Sched, bool ALIGN_EPI = false, bool SP2 = false>
; __device__ __forceinline__ void gemm_phase(PG8_LAS unsigned char* lds, const Gemm g, const Sched& S, const Epi& E) {
;     ...
;             PG8_WAIT_V(8); PG8_WAIT_L(0); PG8_BAR; PG8_MMA(1, 0, At, B0); PG8_MMA(1, 1, At, B1); PG8_BAR; PG8_SCHED;
;             PG8_LDB(B0, 1, 0); PG8_LDB(B1, 1, 1); PG8_SCHED; PG8_LDA(At, 1, 0); PG8_STAGE(PG8_SA(0, 1), a2 + hstep, voffA);
;             PG8_WAIT_V(8); PG8_WAIT_L(0); PG8_BAR; PG8_MMA(0, 0, At, B0); PG8_MMA(0, 1, At, B1); PG8_BAR; PG8_SCHED;
;             PG8_LDA(At, 1, 1); PG8_STAGE(PG8_SB(1, 0), b3, voffB); PG8_STAGE(PG8_SB(1, 1), b3 + hstep, voffB); PG8_STAGE(PG8_SA(1, 0), a3, voffA);
	s_setprio 1
	s_waitcnt lgkmcnt(0)
	v_mfma_f32_16x16x32_bf16 v[60:63], v[146:149], v[190:193], 0
	v_mfma_f32_16x16x32_bf16 v[56:59], v[160:163], v[190:193], 0
	v_mfma_f32_16x16x32_bf16 v[44:47], v[146:149], v[198:201], 0
	v_mfma_f32_16x16x32_bf16 v[40:43], v[160:163], v[198:201], 0
	v_mfma_f32_16x16x32_bf16 v[28:31], v[146:149], v[206:209], 0
	v_mfma_f32_16x16x32_bf16 v[24:27], v[160:163], v[206:209], 0
	v_mfma_f32_16x16x32_bf16 v[12:15], v[146:149], v[214:217], 0
	v_mfma_f32_16x16x32_bf16 v[8:11], v[160:163], v[214:217], 0
	v_mfma_f32_16x16x32_bf16 v[60:63], v[156:159], v[194:197], v[60:63]
	v_mfma_f32_16x16x32_bf16 v[56:59], v[164:167], v[194:197], v[56:59]
	v_mfma_f32_16x16x32_bf16 v[44:47], v[156:159], v[202:205], v[44:47]
	v_mfma_f32_16x16x32_bf16 v[40:43], v[164:167], v[202:205], v[40:43]
	v_mfma_f32_16x16x32_bf16 v[28:31], v[156:159], v[210:213], v[28:31]
	v_mfma_f32_16x16x32_bf16 v[24:27], v[164:167], v[210:213], v[24:27]
	v_mfma_f32_16x16x32_bf16 v[12:15], v[156:159], v[218:221], v[12:15]
	v_mfma_f32_16x16x32_bf16 v[8:11], v[164:167], v[218:221], v[8:11]
	s_setprio 0
	s_setprio 1
	v_mfma_f32_16x16x32_bf16 v[52:55], v[168:171], v[190:193], 0
	v_mfma_f32_16x16x32_bf16 v[48:51], v[176:179], v[190:193], 0
	v_mfma_f32_16x16x32_bf16 v[36:39], v[168:171], v[198:201], 0
	v_mfma_f32_16x16x32_bf16 v[32:35], v[176:179], v[198:201], 0
	v_mfma_f32_16x16x32_bf16 v[20:23], v[168:171], v[206:209], 0
	v_mfma_f32_16x16x32_bf16 v[16:19], v[176:179], v[206:209], 0
	v_mfma_f32_16x16x32_bf16 v[4:7], v[168:171], v[214:217], 0
	v_mfma_f32_16x16x32_bf16 v[0:3], v[176:179], v[214:217], 0
	v_mfma_f32_16x16x32_bf16 v[52:55], v[172:175], v[194:197], v[52:55]
	v_mfma_f32_16x16x32_bf16 v[48:51], v[186:189], v[194:197], v[48:51]
	v_mfma_f32_16x16x32_bf16 v[36:39], v[172:175], v[202:205], v[36:39]
	v_mfma_f32_16x16x32_bf16 v[32:35], v[186:189], v[202:205], v[32:35]
	v_mfma_f32_16x16x32_bf16 v[20:23], v[172:175], v[210:213], v[20:23]
	v_mfma_f32_16x16x32_bf16 v[16:19], v[186:189], v[210:213], v[16:19]
	v_mfma_f32_16x16x32_bf16 v[4:7], v[172:175], v[218:221], v[4:7]
	v_mfma_f32_16x16x32_bf16 v[0:3], v[186:189], v[218:221], v[0:3]
	s_setprio 0
	s_barrier
	s_add_i32 s59, 0, 0x18000
	s_add_i32 s60, 0, 0x1c000
	v_add_u32_e32 v164, s59, v151
	v_add_u32_e32 v185, s60, v151
	ds_read_b128 v[146:149], v164
	ds_read_b128 v[156:159], v164 offset:1024
	ds_read_b128 v[160:163], v164 offset:2048
	ds_read_b128 v[164:167], v164 offset:3072
	ds_read_b128 v[168:171], v185
	ds_read_b128 v[172:175], v185 offset:1024
	ds_read_b128 v[176:179], v185 offset:2048
	ds_read_b128 v[186:189], v185 offset:3072
	s_add_u32 s30, s30, 0x40000
	s_addc_u32 s31, s31, 0
	s_mov_b32 m0, s40
	v_lshl_add_u64 v[228:229], s[30:31], 0, v[134:135]
	ds_read_b128 v[190:193], v154 offset:32768
	ds_read_b128 v[194:197], v154 offset:33792
	ds_read_b128 v[198:201], v154 offset:34816
	ds_read_b128 v[202:205], v154 offset:35840
	ds_read_b128 v[206:209], v154 offset:36864
	ds_read_b128 v[210:213], v154 offset:37888
	ds_read_b128 v[214:217], v154 offset:38912
	ds_read_b128 v[218:221], v154 offset:39936
	global_load_lds_dwordx4 v[228:229], off
	v_lshl_add_u64 v[228:229], s[30:31], 0, v[130:131]
	s_mov_b32 m0, s41
	s_nop 0
	global_load_lds_dwordx4 v[228:229], off
	s_waitcnt vmcnt(8)
	s_waitcnt lgkmcnt(0)
	s_barrier
	s_setprio 1
	s_waitcnt lgkmcnt(0)
	v_mfma_f32_16x16x32_bf16 v[124:127], v[146:149], v[190:193], v[124:127]
	v_mfma_f32_16x16x32_bf16 v[120:123], v[160:163], v[190:193], v[120:123]
	v_mfma_f32_16x16x32_bf16 v[108:111], v[146:149], v[198:201], v[108:111]
	v_mfma_f32_16x16x32_bf16 v[104:107], v[160:163], v[198:201], v[104:107]
	v_mfma_f32_16x16x32_bf16 v[92:95], v[146:149], v[206:209], v[92:95]
	v_mfma_f32_16x16x32_bf16 v[88:91], v[160:163], v[206:209], v[88:91]
	v_mfma_f32_16x16x32_bf16 v[76:79], v[146:149], v[214:217], v[76:79]
	v_mfma_f32_16x16x32_bf16 v[72:75], v[160:163], v[214:217], v[72:75]
	v_mfma_f32_16x16x32_bf16 v[124:127], v[156:159], v[194:197], v[124:127]
	v_mfma_f32_16x16x32_bf16 v[120:123], v[164:167], v[194:197], v[120:123]
	v_mfma_f32_16x16x32_bf16 v[108:111], v[156:159], v[202:205], v[108:111]
	v_mfma_f32_16x16x32_bf16 v[104:107], v[164:167], v[202:205], v[104:107]
	v_mfma_f32_16x16x32_bf16 v[92:95], v[156:159], v[210:213], v[92:95]
	v_mfma_f32_16x16x32_bf16 v[88:91], v[164:167], v[210:213], v[88:91]
	v_mfma_f32_16x16x32_bf16 v[76:79], v[156:159], v[218:221], v[76:79]
	v_mfma_f32_16x16x32_bf16 v[72:75], v[164:167], v[218:221], v[72:75]
	s_setprio 0
	s_setprio 1
	v_mfma_f32_16x16x32_bf16 v[116:119], v[168:171], v[190:193], v[116:119]
	v_mfma_f32_16x16x32_bf16 v[112:115], v[176:179], v[190:193], v[112:115]
	v_mfma_f32_16x16x32_bf16 v[100:103], v[168:171], v[198:201], v[100:103]
	v_mfma_f32_16x16x32_bf16 v[96:99], v[176:179], v[198:201], v[96:99]
	v_mfma_f32_16x16x32_bf16 v[84:87], v[168:171], v[206:209], v[84:87]
	v_mfma_f32_16x16x32_bf16 v[80:83], v[176:179], v[206:209], v[80:83]
	v_mfma_f32_16x16x32_bf16 v[68:71], v[168:171], v[214:217], v[68:71]
	v_mfma_f32_16x16x32_bf16 v[64:67], v[176:179], v[214:217], v[64:67]
	v_mfma_f32_16x16x32_bf16 v[116:119], v[172:175], v[194:197], v[116:119]
	v_mfma_f32_16x16x32_bf16 v[112:115], v[186:189], v[194:197], v[112:115]
	v_mfma_f32_16x16x32_bf16 v[100:103], v[172:175], v[202:205], v[100:103]
	v_mfma_f32_16x16x32_bf16 v[96:99], v[186:189], v[202:205], v[96:99]
	v_mfma_f32_16x16x32_bf16 v[84:87], v[172:175], v[210:213], v[84:87]
	v_mfma_f32_16x16x32_bf16 v[80:83], v[186:189], v[210:213], v[80:83]
	v_mfma_f32_16x16x32_bf16 v[68:71], v[172:175], v[218:221], v[68:71]
	v_mfma_f32_16x16x32_bf16 v[64:67], v[186:189], v[218:221], v[64:67]
	s_setprio 0
	s_barrier
; #define PG8_STAGE(bufoff, gbase, voff) do { _Pragma("unroll") for (int _i = 0; _i < 2; ++_i) \
;         __builtin_amdgcn_global_load_lds((const unsigned*)((const char*)(gbase) + (voff)[_i]), (PG8_LAS unsigned*)(lds + (bufoff) + ldsw + _i * 8192), 16, 0, 0); } while (0)
; #define PG8_LDA(dst, b, h) do { _Pragma("unroll") for (int m = 0; m < 4; ++m) _Pragma("unroll") for (int k = 0; k < 2; ++k) dst[m][k] = *(const PG8_LAS bf16x8*)(lds + PG8_SA(b, h) + aoff + m * 2048 + k * 1024); } while (0)
; #define PG8_MMA(ai, bj, At, Bt) do { __builtin_amdgcn_s_setprio(1); _Pragma("unroll") for (int m = 0; m < 4; ++m) _Pragma("unroll") for (int n = 0; n < 2; ++n) _Pragma("unroll") for (int k = 0; k < 2; ++k) \
;         acc[ai][bj][m][n] = __builtin_amdgcn_mfma_f32_16x16x32_bf16(Bt[n][k], At[m][k], acc[ai][bj][m][n], 0, 0, 0); __builtin_amdgcn_s_setprio(0); } while (0)
; #define PG8_WAIT_V(n) asm volatile("s_waitcnt vmcnt(" #n ")" ::: "memory")
; #define PG8_WAIT_L(n) asm volatile("s_waitcnt lgkmcnt(" #n ")" ::: "memory")
; #define PG8_BAR __builtin_amdgcn_s_barrier()
; #define PG8_SCHED __builtin_amdgcn_sched_barrier(0)
; template <class Epi, class Sched, bool ALIGN_EPI = false, bool SP2 = false>
; __device__ __forceinline__ void gemm_phase(PG8_LAS unsigned char* lds, const Gemm g, const Sched& S, const Epi& E) {
;     ...
;             PG8_LDA(At, 1, 1); PG8_STAGE(PG8_SB(1, 0), b3, voffB); PG8_STAGE(PG8_SB(1, 1), b3 + hstep, voffB); PG8_STAGE(PG8_SA(1, 0), a3, voffA);
;             PG8_WAIT_V(8); PG8_WAIT_L(0); PG8_BAR; PG8_MMA(1, 0, At, B0); PG8_MMA(1, 1, At, B1); PG8_BAR; PG8_SCHED;
	s_add_i32 s30, s59, s35
	v_lshl_add_u64 v[180:181], v[180:181], 0, s[12:13]
	s_mov_b32 m0, s30
	ds_read_b128 v[190:193], v154 offset:49152
	ds_read_b128 v[194:197], v154 offset:50176
	ds_read_b128 v[198:201], v154 offset:51200
	ds_read_b128 v[202:205], v154 offset:52224
	ds_read_b128 v[206:209], v154 offset:53248
	ds_read_b128 v[210:213], v154 offset:54272
	ds_read_b128 v[214:217], v154 offset:55296
	ds_read_b128 v[218:221], v154 offset:56320
	global_load_lds_dwordx4 v[180:181], off
	s_add_i32 m0, s30, 0x2000
	s_add_u32 s28, s28, 0x40080
	v_lshl_add_u64 v[180:181], v[222:223], 0, s[12:13]
	s_addc_u32 s29, s29, 0
	s_add_i32 s30, s60, s35
	global_load_lds_dwordx4 v[180:181], off
	v_lshl_add_u64 v[180:181], s[28:29], 0, v[132:133]
	s_mov_b32 m0, s30
	s_nop 0
	global_load_lds_dwordx4 v[180:181], off
	v_lshl_add_u64 v[180:181], s[28:29], 0, v[128:129]
	s_add_i32 m0, s30, 0x2000
	s_nop 0
	global_load_lds_dwordx4 v[180:181], off
	v_lshl_add_u64 v[180:181], v[224:225], 0, s[12:13]
	s_mov_b32 m0, s42
	s_nop 0
	global_load_lds_dwordx4 v[180:181], off
	v_lshl_add_u64 v[180:181], v[226:227], 0, s[12:13]
	s_mov_b32 m0, s43
	s_nop 0
	global_load_lds_dwordx4 v[180:181], off
	s_waitcnt vmcnt(8)
	s_waitcnt lgkmcnt(0)
	s_barrier
	s_setprio 1
	s_waitcnt lgkmcnt(0)
	v_mfma_f32_16x16x32_bf16 v[60:63], v[146:149], v[190:193], v[60:63]
	v_mfma_f32_16x16x32_bf16 v[56:59], v[160:163], v[190:193], v[56:59]
	v_mfma_f32_16x16x32_bf16 v[44:47], v[146:149], v[198:201], v[44:47]
	v_mfma_f32_16x16x32_bf16 v[40:43], v[160:163], v[198:201], v[40:43]
	v_mfma_f32_16x16x32_bf16 v[28:31], v[146:149], v[206:209], v[28:31]
	v_mfma_f32_16x16x32_bf16 v[24:27], v[160:163], v[206:209], v[24:27]
	v_mfma_f32_16x16x32_bf16 v[12:15], v[146:149], v[214:217], v[12:15]
	v_mfma_f32_16x16x32_bf16 v[8:11], v[160:163], v[214:217], v[8:11]
	v_mfma_f32_16x16x32_bf16 v[60:63], v[156:159], v[194:197], v[60:63]
	v_mfma_f32_16x16x32_bf16 v[56:59], v[164:167], v[194:197], v[56:59]
	v_mfma_f32_16x16x32_bf16 v[44:47], v[156:159], v[202:205], v[44:47]
	v_mfma_f32_16x16x32_bf16 v[40:43], v[164:167], v[202:205], v[40:43]
	v_mfma_f32_16x16x32_bf16 v[28:31], v[156:159], v[210:213], v[28:31]
	v_mfma_f32_16x16x32_bf16 v[24:27], v[164:167], v[210:213], v[24:27]
	v_mfma_f32_16x16x32_bf16 v[12:15], v[156:159], v[218:221], v[12:15]
	v_mfma_f32_16x16x32_bf16 v[8:11], v[164:167], v[218:221], v[8:11]
	s_setprio 0
	s_setprio 1
	v_mfma_f32_16x16x32_bf16 v[52:55], v[168:171], v[190:193], v[52:55]
	v_mfma_f32_16x16x32_bf16 v[48:51], v[176:179], v[190:193], v[48:51]
	v_mfma_f32_16x16x32_bf16 v[36:39], v[168:171], v[198:201], v[36:39]
	v_mfma_f32_16x16x32_bf16 v[32:35], v[176:179], v[198:201], v[32:35]
	v_mfma_f32_16x16x32_bf16 v[20:23], v[168:171], v[206:209], v[20:23]
	v_mfma_f32_16x16x32_bf16 v[16:19], v[176:179], v[206:209], v[16:19]
	v_mfma_f32_16x16x32_bf16 v[4:7], v[168:171], v[214:217], v[4:7]
	v_mfma_f32_16x16x32_bf16 v[0:3], v[176:179], v[214:217], v[0:3]
	v_mfma_f32_16x16x32_bf16 v[52:55], v[172:175], v[194:197], v[52:55]
	v_mfma_f32_16x16x32_bf16 v[48:51], v[186:189], v[194:197], v[48:51]
	v_mfma_f32_16x16x32_bf16 v[36:39], v[172:175], v[202:205], v[36:39]
	v_mfma_f32_16x16x32_bf16 v[32:35], v[186:189], v[202:205], v[32:35]
	v_mfma_f32_16x16x32_bf16 v[20:23], v[172:175], v[210:213], v[20:23]
	v_mfma_f32_16x16x32_bf16 v[16:19], v[186:189], v[210:213], v[16:19]
	v_mfma_f32_16x16x32_bf16 v[4:7], v[172:175], v[218:221], v[4:7]
	v_mfma_f32_16x16x32_bf16 v[0:3], v[186:189], v[218:221], v[0:3]
	s_setprio 0
	s_barrier
	s_add_i32 s58, s58, 2
	s_add_u32 s26, s26, 0x100
	s_addc_u32 s27, s27, 0
	s_add_u32 s56, s56, 0x100
	s_addc_u32 s57, s57, 0
	s_cmp_gt_u32 s58, 13

; DI unsigned cvtpk(float lo, float hi) { f32x2_t v = {lo, hi}; bf16x2_t b = __builtin_convertvector(v, bf16x2_t); return __builtin_bit_cast(unsigned, b); }
; DI float silu_f(float x) { return x * __builtin_amdgcn_rcpf(1.0f + __expf(-x)); }
;     DI void operator()(const f32x4 (&acc)[2][2][4][2], const Unit& u, int wr, int wc, int fr, int fq) const {
;     ...
;         for (int ai = 0; ai < 2; ++ai)
; #pragma unroll
;             for (int m = 0; m < 4; ++m) {
;                 const int row = u.pm * 256 + 128 * ai + 64 * wr + 16 * m + fr;
;                 const float* sp = SSQ + (size_t)row * 16;
;                 const f32x4 s0 = *(const f32x4*)sp, s1 = *(const f32x4*)(sp + 4), s2 = *(const f32x4*)(sp + 8), s3 = *(const f32x4*)(sp + 12);
;                 float ss = 0.f;
; #pragma unroll
;                 for (int i = 0; i < 4; ++i) ss += s0[i] + s1[i] + s2[i] + s3[i];
;                 const float rs = rsqrtf(ss * (1.0f / DM) + EPS);
;                 float a[8];
; #pragma unroll
;                 for (int n = 0; n < 2; ++n)
; #pragma unroll
;                     for (int t = 0; t < 4; ++t) a[4 * n + t] = silu_f(acc[ai][0][m][n][t] * rs) * (acc[ai][1][m][n][t] * rs);
;                 u32x4 w; w.x = cvtpk(a[0], a[1]); w.y = cvtpk(a[2], a[3]); w.z = cvtpk(a[4], a[5]); w.w = cvtpk(a[6], a[7]);
;                 __builtin_nontemporal_store(w, (u32x4*)(ACT + (size_t)row * DFF + u.pn * 128 + 32 * wc + 8 * fq));
.LBB0_863:
	v_lshl_add_u32 v148, s24, 8, v150
	v_ashrrev_i32_e32 v149, 31, v148
	v_lshlrev_b64 v[146:147], 6, v[148:149]
	v_pk_add_f32 v[186:187], v[230:231], v[234:235]
	v_pk_add_f32 v[188:189], v[232:233], v[236:237]
	v_pk_add_f32 v[186:187], v[238:239], v[186:187]
	v_pk_add_f32 v[188:189], v[240:241], v[188:189]
	v_pk_add_f32 v[186:187], v[242:243], v[186:187]
	v_pk_add_f32 v[188:189], v[244:245], v[188:189]
	s_and_b64 vcc, exec, s[6:7]
	s_cbranch_vccz .Lp4_noq
	s_lshl_b32 s59, s18, 14
	v_add_u32_e32 v248, s59, v246
	global_load_dwordx4 v[230:233], v248, s[0:1]
	global_load_dwordx4 v[234:237], v248, s[0:1] offset:16
	global_load_dwordx4 v[238:241], v248, s[0:1] offset:32
	global_load_dwordx4 v[242:245], v248, s[0:1] offset:48
.Lp4_noq:
	v_add_f32_e32 v190, 0, v186
	v_add_f32_e32 v190, v187, v190
	v_add_f32_e32 v190, v188, v190
	v_add_f32_e32 v190, v189, v190
	v_fmamk_f32 v190, v190, 0x3a800000, v155
	v_mul_f32_e32 v191, 0x4b800000, v190
	v_cmp_gt_f32_e32 vcc, s47, v190
	s_nop 1
	v_cndmask_b32_e32 v190, v190, v191, vcc
	v_rsq_f32_e32 v190, v190
	s_nop 1
	v_mul_f32_e32 v191, 0x45800000, v190
	v_cndmask_b32_e32 v190, v190, v191, vcc
	ds_write_b32 v247, v190
	s_waitcnt lgkmcnt(0)
	s_barrier
	v_mov_b32_e32 v202, 0x20000
	v_lshl_add_u32 v202, v150, 2, v202
	ds_read_b32 v186, v202 offset:0
	ds_read_b32 v188, v202 offset:64
	ds_read_b32 v190, v202 offset:128
	ds_read_b32 v192, v202 offset:192
	ds_read_b32 v194, v202 offset:512
	ds_read_b32 v196, v202 offset:576
	ds_read_b32 v198, v202 offset:640
	ds_read_b32 v200, v202 offset:704
	s_lshl_b32 s24, s25, 7
	v_mov_b64_e32 v[146:147], s[52:53]
	s_ashr_i32 s25, s24, 31
	v_mad_i64_i32 v[172:173], s[26:27], v148, s48, v[146:147]
	s_lshl_b64 s[24:25], s[24:25], 1
	v_lshl_add_u64 v[172:173], v[172:173], 0, s[24:25]
	v_or_b32_e32 v174, 16, v148
	v_ashrrev_i32_e32 v175, 31, v174
	v_lshlrev_b64 v[176:177], 6, v[174:175]
	v_lshl_add_u64 v[156:157], v[172:173], 0, s[8:9]
	v_lshl_add_u64 v[156:157], v[156:157], 0, v[136:137]
	s_waitcnt lgkmcnt(7)
	v_pk_mul_f32 v[124:125], v[124:125], v[186:187] op_sel_hi:[1,0]
	v_pk_mul_f32 v[126:127], v[126:127], v[186:187] op_sel_hi:[1,0]
	v_pk_mul_f32 v[120:121], v[120:121], v[186:187] op_sel_hi:[1,0]
	v_pk_mul_f32 v[122:123], v[122:123], v[186:187] op_sel_hi:[1,0]
	v_pk_mul_f32 v[116:117], v[116:117], v[186:187] op_sel_hi:[1,0]
	v_pk_mul_f32 v[118:119], v[118:119], v[186:187] op_sel_hi:[1,0]
	v_pk_mul_f32 v[112:113], v[112:113], v[186:187] op_sel_hi:[1,0]
	v_pk_mul_f32 v[114:115], v[114:115], v[186:187] op_sel_hi:[1,0]
	v_mul_f32_e32 v149, 0xbfb8aa3b, v124
	v_mul_f32_e32 v160, 0xbfb8aa3b, v125
	v_mul_f32_e32 v161, 0xbfb8aa3b, v126
	v_mul_f32_e32 v162, 0xbfb8aa3b, v127
	v_mul_f32_e32 v163, 0xbfb8aa3b, v120
	v_mul_f32_e32 v164, 0xbfb8aa3b, v121
	v_mul_f32_e32 v165, 0xbfb8aa3b, v122
	v_mul_f32_e32 v166, 0xbfb8aa3b, v123
	v_exp_f32_e32 v149, v149
	v_exp_f32_e32 v160, v160
	v_exp_f32_e32 v161, v161
	v_exp_f32_e32 v162, v162
	v_exp_f32_e32 v163, v163
	v_exp_f32_e32 v164, v164
	v_exp_f32_e32 v165, v165
	v_exp_f32_e32 v166, v166
	v_add_f32_e32 v149, 1.0, v149
	v_add_f32_e32 v167, 1.0, v160
	v_add_f32_e32 v168, 1.0, v161
	v_add_f32_e32 v169, 1.0, v162
	v_add_f32_e32 v170, 1.0, v163
	v_add_f32_e32 v171, 1.0, v164
	v_add_f32_e32 v172, 1.0, v165
	v_add_f32_e32 v173, 1.0, v166
	v_rcp_f32_e32 v160, v149
	v_rcp_f32_e32 v161, v167
	v_rcp_f32_e32 v162, v168
	v_rcp_f32_e32 v163, v169
	v_rcp_f32_e32 v164, v170
	v_rcp_f32_e32 v165, v171
	v_rcp_f32_e32 v166, v172
	v_rcp_f32_e32 v167, v173
	v_pk_mul_f32 v[124:125], v[124:125], v[160:161]
	v_pk_mul_f32 v[126:127], v[126:127], v[162:163]
	v_pk_mul_f32 v[120:121], v[120:121], v[164:165]
	v_pk_mul_f32 v[122:123], v[122:123], v[166:167]
	v_pk_mul_f32 v[116:117], v[116:117], v[124:125]
	v_pk_mul_f32 v[118:119], v[118:119], v[126:127]
	v_pk_mul_f32 v[120:121], v[112:113], v[120:121]
	v_pk_mul_f32 v[122:123], v[114:115], v[122:123]
	v_cvt_pk_bf16_f32 v112, v116, v117
	v_cvt_pk_bf16_f32 v113, v118, v119
	v_cvt_pk_bf16_f32 v114, v120, v121
	v_cvt_pk_bf16_f32 v115, v122, v123
	global_store_dwordx4 v[156:157], v[112:115], off nt
	v_mad_i64_i32 v[158:159], s[26:27], v174, s48, v[146:147]
	v_or_b32_e32 v156, 32, v148
	v_lshl_add_u64 v[158:159], v[158:159], 0, s[24:25]
	v_ashrrev_i32_e32 v157, 31, v156
	v_lshlrev_b64 v[160:161], 6, v[156:157]
	v_lshl_add_u64 v[112:113], v[158:159], 0, s[8:9]
	v_lshl_add_u64 v[112:113], v[112:113], 0, v[136:137]
	s_waitcnt lgkmcnt(6)
	v_pk_mul_f32 v[108:109], v[108:109], v[188:189] op_sel_hi:[1,0]
	v_pk_mul_f32 v[110:111], v[110:111], v[188:189] op_sel_hi:[1,0]
	v_pk_mul_f32 v[104:105], v[104:105], v[188:189] op_sel_hi:[1,0]
	v_pk_mul_f32 v[106:107], v[106:107], v[188:189] op_sel_hi:[1,0]
	v_pk_mul_f32 v[100:101], v[100:101], v[188:189] op_sel_hi:[1,0]
	v_pk_mul_f32 v[102:103], v[102:103], v[188:189] op_sel_hi:[1,0]
	v_pk_mul_f32 v[96:97], v[96:97], v[188:189] op_sel_hi:[1,0]
	v_pk_mul_f32 v[98:99], v[98:99], v[188:189] op_sel_hi:[1,0]
	v_mul_f32_e32 v116, 0xbfb8aa3b, v108
	v_mul_f32_e32 v117, 0xbfb8aa3b, v109
	v_mul_f32_e32 v118, 0xbfb8aa3b, v110
	v_mul_f32_e32 v119, 0xbfb8aa3b, v111
	v_mul_f32_e32 v120, 0xbfb8aa3b, v104
	v_mul_f32_e32 v121, 0xbfb8aa3b, v105
	v_mul_f32_e32 v122, 0xbfb8aa3b, v106
	v_mul_f32_e32 v123, 0xbfb8aa3b, v107
	v_exp_f32_e32 v116, v116
	v_exp_f32_e32 v117, v117
	v_exp_f32_e32 v118, v118
	v_exp_f32_e32 v119, v119
	v_exp_f32_e32 v120, v120
	v_exp_f32_e32 v121, v121
	v_exp_f32_e32 v122, v122
	v_exp_f32_e32 v123, v123
	v_add_f32_e32 v116, 1.0, v116
	v_add_f32_e32 v117, 1.0, v117
	v_add_f32_e32 v118, 1.0, v118
	v_add_f32_e32 v119, 1.0, v119
	v_add_f32_e32 v120, 1.0, v120
	v_add_f32_e32 v121, 1.0, v121
	v_add_f32_e32 v122, 1.0, v122
	v_add_f32_e32 v123, 1.0, v123
	v_rcp_f32_e32 v116, v116
	v_rcp_f32_e32 v117, v117
	v_rcp_f32_e32 v118, v118
	v_rcp_f32_e32 v119, v119
	v_rcp_f32_e32 v120, v120
	v_rcp_f32_e32 v121, v121
	v_rcp_f32_e32 v122, v122
	v_rcp_f32_e32 v123, v123
	v_pk_mul_f32 v[108:109], v[108:109], v[116:117]
	v_pk_mul_f32 v[110:111], v[110:111], v[118:119]
	v_pk_mul_f32 v[104:105], v[104:105], v[120:121]
	v_pk_mul_f32 v[106:107], v[106:107], v[122:123]
	v_pk_mul_f32 v[100:101], v[100:101], v[108:109]
	v_pk_mul_f32 v[102:103], v[102:103], v[110:111]
	v_pk_mul_f32 v[104:105], v[96:97], v[104:105]
	v_pk_mul_f32 v[106:107], v[98:99], v[106:107]
	v_cvt_pk_bf16_f32 v96, v100, v101
	v_cvt_pk_bf16_f32 v97, v102, v103
	v_cvt_pk_bf16_f32 v98, v104, v105
	v_cvt_pk_bf16_f32 v99, v106, v107
	global_store_dwordx4 v[112:113], v[96:99], off nt
	v_mad_i64_i32 v[114:115], s[26:27], v156, s48, v[146:147]
	v_or_b32_e32 v112, 48, v148
	v_lshl_add_u64 v[114:115], v[114:115], 0, s[24:25]
	v_ashrrev_i32_e32 v113, 31, v112
	v_lshlrev_b64 v[116:117], 6, v[112:113]
	v_lshl_add_u64 v[96:97], v[114:115], 0, s[8:9]
	v_lshl_add_u64 v[96:97], v[96:97], 0, v[136:137]
	s_waitcnt lgkmcnt(5)
; DI unsigned cvtpk(float lo, float hi) { f32x2_t v = {lo, hi}; bf16x2_t b = __builtin_convertvector(v, bf16x2_t); return __builtin_bit_cast(unsigned, b); }
; DI float silu_f(float x) { return x * __builtin_amdgcn_rcpf(1.0f + __expf(-x)); }
;     DI void operator()(const f32x4 (&acc)[2][2][4][2], const Unit& u, int wr, int wc, int fr, int fq) const {
;     ...
;                 float a[8];
; #pragma unroll
;                 for (int n = 0; n < 2; ++n)
; #pragma unroll
;                     for (int t = 0; t < 4; ++t) a[4 * n + t] = silu_f(acc[ai][0][m][n][t] * rs) * (acc[ai][1][m][n][t] * rs);
;                 u32x4 w; w.x = cvtpk(a[0], a[1]); w.y = cvtpk(a[2], a[3]); w.z = cvtpk(a[4], a[5]); w.w = cvtpk(a[6], a[7]);
;                 __builtin_nontemporal_store(w, (u32x4*)(ACT + (size_t)row * DFF + u.pn * 128 + 32 * wc + 8 * fq));
	v_pk_mul_f32 v[92:93], v[92:93], v[190:191] op_sel_hi:[1,0]
	v_pk_mul_f32 v[94:95], v[94:95], v[190:191] op_sel_hi:[1,0]
	v_pk_mul_f32 v[88:89], v[88:89], v[190:191] op_sel_hi:[1,0]
	v_pk_mul_f32 v[90:91], v[90:91], v[190:191] op_sel_hi:[1,0]
	v_pk_mul_f32 v[84:85], v[84:85], v[190:191] op_sel_hi:[1,0]
	v_pk_mul_f32 v[86:87], v[86:87], v[190:191] op_sel_hi:[1,0]
	v_pk_mul_f32 v[80:81], v[80:81], v[190:191] op_sel_hi:[1,0]
	v_pk_mul_f32 v[82:83], v[82:83], v[190:191] op_sel_hi:[1,0]
	v_mul_f32_e32 v100, 0xbfb8aa3b, v92
	v_mul_f32_e32 v101, 0xbfb8aa3b, v93
	v_mul_f32_e32 v102, 0xbfb8aa3b, v94
	v_mul_f32_e32 v103, 0xbfb8aa3b, v95
	v_mul_f32_e32 v104, 0xbfb8aa3b, v88
	v_mul_f32_e32 v105, 0xbfb8aa3b, v89
	v_mul_f32_e32 v106, 0xbfb8aa3b, v90
	v_mul_f32_e32 v107, 0xbfb8aa3b, v91
	v_exp_f32_e32 v100, v100
	v_exp_f32_e32 v101, v101
	v_exp_f32_e32 v102, v102
	v_exp_f32_e32 v103, v103
	v_exp_f32_e32 v104, v104
	v_exp_f32_e32 v105, v105
	v_exp_f32_e32 v106, v106
	v_exp_f32_e32 v107, v107
	v_add_f32_e32 v100, 1.0, v100
	v_add_f32_e32 v101, 1.0, v101
	v_add_f32_e32 v102, 1.0, v102
	v_add_f32_e32 v103, 1.0, v103
	v_add_f32_e32 v104, 1.0, v104
	v_add_f32_e32 v105, 1.0, v105
	v_add_f32_e32 v106, 1.0, v106
	v_add_f32_e32 v107, 1.0, v107
	v_rcp_f32_e32 v100, v100
	v_rcp_f32_e32 v101, v101
	v_rcp_f32_e32 v102, v102
	v_rcp_f32_e32 v103, v103
	v_rcp_f32_e32 v104, v104
	v_rcp_f32_e32 v105, v105
	v_rcp_f32_e32 v106, v106
	v_rcp_f32_e32 v107, v107
	v_pk_mul_f32 v[92:93], v[92:93], v[100:101]
	v_pk_mul_f32 v[94:95], v[94:95], v[102:103]
	v_pk_mul_f32 v[88:89], v[88:89], v[104:105]
	v_pk_mul_f32 v[90:91], v[90:91], v[106:107]
	v_pk_mul_f32 v[84:85], v[84:85], v[92:93]
	v_pk_mul_f32 v[86:87], v[86:87], v[94:95]
	v_pk_mul_f32 v[88:89], v[80:81], v[88:89]
	v_pk_mul_f32 v[90:91], v[82:83], v[90:91]
	v_cvt_pk_bf16_f32 v80, v84, v85
	v_cvt_pk_bf16_f32 v81, v86, v87
	v_cvt_pk_bf16_f32 v82, v88, v89
	v_cvt_pk_bf16_f32 v83, v90, v91
	global_store_dwordx4 v[96:97], v[80:83], off nt
	v_mad_i64_i32 v[98:99], s[26:27], v112, s48, v[146:147]
	v_add_u32_e32 v96, 0x80, v148
	v_lshl_add_u64 v[98:99], v[98:99], 0, s[24:25]
	v_ashrrev_i32_e32 v97, 31, v96
	v_lshlrev_b64 v[100:101], 6, v[96:97]
	v_lshl_add_u64 v[80:81], v[98:99], 0, s[8:9]
	v_lshl_add_u64 v[80:81], v[80:81], 0, v[136:137]
	s_waitcnt lgkmcnt(4)
	v_pk_mul_f32 v[76:77], v[76:77], v[192:193] op_sel_hi:[1,0]
	v_pk_mul_f32 v[78:79], v[78:79], v[192:193] op_sel_hi:[1,0]
	v_pk_mul_f32 v[72:73], v[72:73], v[192:193] op_sel_hi:[1,0]
	v_pk_mul_f32 v[74:75], v[74:75], v[192:193] op_sel_hi:[1,0]
	v_pk_mul_f32 v[68:69], v[68:69], v[192:193] op_sel_hi:[1,0]
	v_pk_mul_f32 v[70:71], v[70:71], v[192:193] op_sel_hi:[1,0]
	v_pk_mul_f32 v[64:65], v[64:65], v[192:193] op_sel_hi:[1,0]
	v_pk_mul_f32 v[66:67], v[66:67], v[192:193] op_sel_hi:[1,0]
	v_mul_f32_e32 v84, 0xbfb8aa3b, v76
	v_mul_f32_e32 v85, 0xbfb8aa3b, v77
	v_mul_f32_e32 v86, 0xbfb8aa3b, v78
	v_mul_f32_e32 v87, 0xbfb8aa3b, v79
	v_mul_f32_e32 v88, 0xbfb8aa3b, v72
	v_mul_f32_e32 v89, 0xbfb8aa3b, v73
	v_mul_f32_e32 v90, 0xbfb8aa3b, v74
	v_mul_f32_e32 v91, 0xbfb8aa3b, v75
	v_exp_f32_e32 v84, v84
	v_exp_f32_e32 v85, v85
	v_exp_f32_e32 v86, v86
	v_exp_f32_e32 v87, v87
	v_exp_f32_e32 v88, v88
	v_exp_f32_e32 v89, v89
	v_exp_f32_e32 v90, v90
	v_exp_f32_e32 v91, v91
	v_add_f32_e32 v84, 1.0, v84
	v_add_f32_e32 v85, 1.0, v85
	v_add_f32_e32 v86, 1.0, v86
	v_add_f32_e32 v87, 1.0, v87
	v_add_f32_e32 v88, 1.0, v88
	v_add_f32_e32 v89, 1.0, v89
	v_add_f32_e32 v90, 1.0, v90
	v_add_f32_e32 v91, 1.0, v91
	v_rcp_f32_e32 v84, v84
	v_rcp_f32_e32 v85, v85
	v_rcp_f32_e32 v86, v86
	v_rcp_f32_e32 v87, v87
	v_rcp_f32_e32 v88, v88
	v_rcp_f32_e32 v89, v89
	v_rcp_f32_e32 v90, v90
	v_rcp_f32_e32 v91, v91
	v_pk_mul_f32 v[76:77], v[76:77], v[84:85]
	v_pk_mul_f32 v[78:79], v[78:79], v[86:87]
	v_pk_mul_f32 v[72:73], v[72:73], v[88:89]
	v_pk_mul_f32 v[74:75], v[74:75], v[90:91]
	v_pk_mul_f32 v[68:69], v[68:69], v[76:77]
	v_pk_mul_f32 v[70:71], v[70:71], v[78:79]
	v_pk_mul_f32 v[72:73], v[64:65], v[72:73]
	v_pk_mul_f32 v[74:75], v[66:67], v[74:75]
	v_cvt_pk_bf16_f32 v64, v68, v69
	v_cvt_pk_bf16_f32 v65, v70, v71
	v_cvt_pk_bf16_f32 v66, v72, v73
	v_cvt_pk_bf16_f32 v67, v74, v75
	global_store_dwordx4 v[80:81], v[64:67], off nt
	v_mad_i64_i32 v[82:83], s[26:27], v96, s48, v[146:147]
	v_add_u32_e32 v80, 0x90, v148
	v_lshl_add_u64 v[82:83], v[82:83], 0, s[24:25]
	v_ashrrev_i32_e32 v81, 31, v80
	v_lshlrev_b64 v[84:85], 6, v[80:81]
	v_lshl_add_u64 v[64:65], v[82:83], 0, s[8:9]
	v_lshl_add_u64 v[64:65], v[64:65], 0, v[136:137]
	s_waitcnt lgkmcnt(3)
; DI unsigned cvtpk(float lo, float hi) { f32x2_t v = {lo, hi}; bf16x2_t b = __builtin_convertvector(v, bf16x2_t); return __builtin_bit_cast(unsigned, b); }
; DI float silu_f(float x) { return x * __builtin_amdgcn_rcpf(1.0f + __expf(-x)); }
;     DI void operator()(const f32x4 (&acc)[2][2][4][2], const Unit& u, int wr, int wc, int fr, int fq) const {
;     ...
;                 float a[8];
; #pragma unroll
;                 for (int n = 0; n < 2; ++n)
; #pragma unroll
;                     for (int t = 0; t < 4; ++t) a[4 * n + t] = silu_f(acc[ai][0][m][n][t] * rs) * (acc[ai][1][m][n][t] * rs);
;                 u32x4 w; w.x = cvtpk(a[0], a[1]); w.y = cvtpk(a[2], a[3]); w.z = cvtpk(a[4], a[5]); w.w = cvtpk(a[6], a[7]);
;                 __builtin_nontemporal_store(w, (u32x4*)(ACT + (size_t)row * DFF + u.pn * 128 + 32 * wc + 8 * fq));
	v_pk_mul_f32 v[60:61], v[60:61], v[194:195] op_sel_hi:[1,0]
	v_pk_mul_f32 v[62:63], v[62:63], v[194:195] op_sel_hi:[1,0]
	v_pk_mul_f32 v[56:57], v[56:57], v[194:195] op_sel_hi:[1,0]
	v_pk_mul_f32 v[58:59], v[58:59], v[194:195] op_sel_hi:[1,0]
	v_pk_mul_f32 v[52:53], v[52:53], v[194:195] op_sel_hi:[1,0]
	v_pk_mul_f32 v[54:55], v[54:55], v[194:195] op_sel_hi:[1,0]
	v_pk_mul_f32 v[48:49], v[48:49], v[194:195] op_sel_hi:[1,0]
	v_pk_mul_f32 v[50:51], v[50:51], v[194:195] op_sel_hi:[1,0]
	v_mul_f32_e32 v68, 0xbfb8aa3b, v60
	v_mul_f32_e32 v69, 0xbfb8aa3b, v61
	v_mul_f32_e32 v70, 0xbfb8aa3b, v62
	v_mul_f32_e32 v71, 0xbfb8aa3b, v63
	v_mul_f32_e32 v72, 0xbfb8aa3b, v56
	v_mul_f32_e32 v73, 0xbfb8aa3b, v57
	v_mul_f32_e32 v74, 0xbfb8aa3b, v58
	v_mul_f32_e32 v75, 0xbfb8aa3b, v59
	v_exp_f32_e32 v68, v68
	v_exp_f32_e32 v69, v69
	v_exp_f32_e32 v70, v70
	v_exp_f32_e32 v71, v71
	v_exp_f32_e32 v72, v72
	v_exp_f32_e32 v73, v73
	v_exp_f32_e32 v74, v74
	v_exp_f32_e32 v75, v75
	v_add_f32_e32 v68, 1.0, v68
	v_add_f32_e32 v69, 1.0, v69
	v_add_f32_e32 v70, 1.0, v70
	v_add_f32_e32 v71, 1.0, v71
	v_add_f32_e32 v72, 1.0, v72
	v_add_f32_e32 v73, 1.0, v73
	v_add_f32_e32 v74, 1.0, v74
	v_add_f32_e32 v75, 1.0, v75
	v_rcp_f32_e32 v68, v68
	v_rcp_f32_e32 v69, v69
	v_rcp_f32_e32 v70, v70
	v_rcp_f32_e32 v71, v71
	v_rcp_f32_e32 v72, v72
	v_rcp_f32_e32 v73, v73
	v_rcp_f32_e32 v74, v74
	v_rcp_f32_e32 v75, v75
	v_pk_mul_f32 v[60:61], v[60:61], v[68:69]
	v_pk_mul_f32 v[62:63], v[62:63], v[70:71]
	v_pk_mul_f32 v[56:57], v[56:57], v[72:73]
	v_pk_mul_f32 v[58:59], v[58:59], v[74:75]
	v_pk_mul_f32 v[52:53], v[52:53], v[60:61]
	v_pk_mul_f32 v[54:55], v[54:55], v[62:63]
	v_pk_mul_f32 v[56:57], v[48:49], v[56:57]
	v_pk_mul_f32 v[58:59], v[50:51], v[58:59]
	v_cvt_pk_bf16_f32 v48, v52, v53
	v_cvt_pk_bf16_f32 v49, v54, v55
	v_cvt_pk_bf16_f32 v50, v56, v57
	v_cvt_pk_bf16_f32 v51, v58, v59
	global_store_dwordx4 v[64:65], v[48:51], off nt
	v_mad_i64_i32 v[66:67], s[26:27], v80, s48, v[146:147]
	v_add_u32_e32 v64, 0xa0, v148
	v_lshl_add_u64 v[66:67], v[66:67], 0, s[24:25]
	v_ashrrev_i32_e32 v65, 31, v64
	v_lshlrev_b64 v[68:69], 6, v[64:65]
	v_lshl_add_u64 v[48:49], v[66:67], 0, s[8:9]
	v_lshl_add_u64 v[48:49], v[48:49], 0, v[136:137]
	s_waitcnt lgkmcnt(2)
	v_pk_mul_f32 v[44:45], v[44:45], v[196:197] op_sel_hi:[1,0]
	v_pk_mul_f32 v[46:47], v[46:47], v[196:197] op_sel_hi:[1,0]
	v_pk_mul_f32 v[40:41], v[40:41], v[196:197] op_sel_hi:[1,0]
	v_pk_mul_f32 v[42:43], v[42:43], v[196:197] op_sel_hi:[1,0]
	v_pk_mul_f32 v[36:37], v[36:37], v[196:197] op_sel_hi:[1,0]
	v_pk_mul_f32 v[38:39], v[38:39], v[196:197] op_sel_hi:[1,0]
	v_pk_mul_f32 v[32:33], v[32:33], v[196:197] op_sel_hi:[1,0]
	v_pk_mul_f32 v[34:35], v[34:35], v[196:197] op_sel_hi:[1,0]
	v_mul_f32_e32 v52, 0xbfb8aa3b, v44
	v_mul_f32_e32 v53, 0xbfb8aa3b, v45
	v_mul_f32_e32 v54, 0xbfb8aa3b, v46
	v_mul_f32_e32 v55, 0xbfb8aa3b, v47
	v_mul_f32_e32 v56, 0xbfb8aa3b, v40
	v_mul_f32_e32 v57, 0xbfb8aa3b, v41
	v_mul_f32_e32 v58, 0xbfb8aa3b, v42
	v_mul_f32_e32 v59, 0xbfb8aa3b, v43
	v_exp_f32_e32 v52, v52
	v_exp_f32_e32 v53, v53
	v_exp_f32_e32 v54, v54
	v_exp_f32_e32 v55, v55
	v_exp_f32_e32 v56, v56
	v_exp_f32_e32 v57, v57
	v_exp_f32_e32 v58, v58
	v_exp_f32_e32 v59, v59
	v_add_f32_e32 v52, 1.0, v52
	v_add_f32_e32 v53, 1.0, v53
	v_add_f32_e32 v54, 1.0, v54
	v_add_f32_e32 v55, 1.0, v55
	v_add_f32_e32 v56, 1.0, v56
	v_add_f32_e32 v57, 1.0, v57
	v_add_f32_e32 v58, 1.0, v58
	v_add_f32_e32 v59, 1.0, v59
	v_rcp_f32_e32 v52, v52
	v_rcp_f32_e32 v53, v53
	v_rcp_f32_e32 v54, v54
	v_rcp_f32_e32 v55, v55
	v_rcp_f32_e32 v56, v56
	v_rcp_f32_e32 v57, v57
	v_rcp_f32_e32 v58, v58
	v_rcp_f32_e32 v59, v59
	v_pk_mul_f32 v[44:45], v[44:45], v[52:53]
	v_pk_mul_f32 v[46:47], v[46:47], v[54:55]
	v_pk_mul_f32 v[40:41], v[40:41], v[56:57]
	v_pk_mul_f32 v[42:43], v[42:43], v[58:59]
	v_pk_mul_f32 v[36:37], v[36:37], v[44:45]
	v_pk_mul_f32 v[38:39], v[38:39], v[46:47]
	v_pk_mul_f32 v[40:41], v[32:33], v[40:41]
	v_pk_mul_f32 v[42:43], v[34:35], v[42:43]
	v_cvt_pk_bf16_f32 v32, v36, v37
	v_cvt_pk_bf16_f32 v33, v38, v39
	v_cvt_pk_bf16_f32 v34, v40, v41
	v_cvt_pk_bf16_f32 v35, v42, v43
	global_store_dwordx4 v[48:49], v[32:35], off nt
	v_mad_i64_i32 v[50:51], s[26:27], v64, s48, v[146:147]
	v_add_u32_e32 v48, 0xb0, v148
	v_lshl_add_u64 v[50:51], v[50:51], 0, s[24:25]
	v_ashrrev_i32_e32 v49, 31, v48
	v_lshlrev_b64 v[52:53], 6, v[48:49]
	v_lshl_add_u64 v[32:33], v[50:51], 0, s[8:9]
	v_lshl_add_u64 v[32:33], v[32:33], 0, v[136:137]
	s_waitcnt lgkmcnt(1)
; DI unsigned cvtpk(float lo, float hi) { f32x2_t v = {lo, hi}; bf16x2_t b = __builtin_convertvector(v, bf16x2_t); return __builtin_bit_cast(unsigned, b); }
; DI float silu_f(float x) { return x * __builtin_amdgcn_rcpf(1.0f + __expf(-x)); }
;     DI void operator()(const f32x4 (&acc)[2][2][4][2], const Unit& u, int wr, int wc, int fr, int fq) const {
;     ...
;                 float a[8];
; #pragma unroll
;                 for (int n = 0; n < 2; ++n)
; #pragma unroll
;                     for (int t = 0; t < 4; ++t) a[4 * n + t] = silu_f(acc[ai][0][m][n][t] * rs) * (acc[ai][1][m][n][t] * rs);
;                 u32x4 w; w.x = cvtpk(a[0], a[1]); w.y = cvtpk(a[2], a[3]); w.z = cvtpk(a[4], a[5]); w.w = cvtpk(a[6], a[7]);
;                 __builtin_nontemporal_store(w, (u32x4*)(ACT + (size_t)row * DFF + u.pn * 128 + 32 * wc + 8 * fq));
	v_pk_mul_f32 v[28:29], v[28:29], v[198:199] op_sel_hi:[1,0]
	v_pk_mul_f32 v[30:31], v[30:31], v[198:199] op_sel_hi:[1,0]
	v_pk_mul_f32 v[24:25], v[24:25], v[198:199] op_sel_hi:[1,0]
	v_pk_mul_f32 v[26:27], v[26:27], v[198:199] op_sel_hi:[1,0]
	v_pk_mul_f32 v[20:21], v[20:21], v[198:199] op_sel_hi:[1,0]
	v_pk_mul_f32 v[22:23], v[22:23], v[198:199] op_sel_hi:[1,0]
	v_pk_mul_f32 v[16:17], v[16:17], v[198:199] op_sel_hi:[1,0]
	v_pk_mul_f32 v[18:19], v[18:19], v[198:199] op_sel_hi:[1,0]
	v_mul_f32_e32 v36, 0xbfb8aa3b, v28
	v_mul_f32_e32 v37, 0xbfb8aa3b, v29
	v_mul_f32_e32 v38, 0xbfb8aa3b, v30
	v_mul_f32_e32 v39, 0xbfb8aa3b, v31
	v_mul_f32_e32 v40, 0xbfb8aa3b, v24
	v_mul_f32_e32 v41, 0xbfb8aa3b, v25
	v_mul_f32_e32 v42, 0xbfb8aa3b, v26
	v_mul_f32_e32 v43, 0xbfb8aa3b, v27
	v_exp_f32_e32 v36, v36
	v_exp_f32_e32 v37, v37
	v_exp_f32_e32 v38, v38
	v_exp_f32_e32 v39, v39
	v_exp_f32_e32 v40, v40
	v_exp_f32_e32 v41, v41
	v_exp_f32_e32 v42, v42
	v_exp_f32_e32 v43, v43
	v_add_f32_e32 v36, 1.0, v36
	v_add_f32_e32 v37, 1.0, v37
	v_add_f32_e32 v38, 1.0, v38
	v_add_f32_e32 v39, 1.0, v39
	v_add_f32_e32 v40, 1.0, v40
	v_add_f32_e32 v41, 1.0, v41
	v_add_f32_e32 v42, 1.0, v42
	v_add_f32_e32 v43, 1.0, v43
	v_rcp_f32_e32 v36, v36
	v_rcp_f32_e32 v37, v37
	v_rcp_f32_e32 v38, v38
	v_rcp_f32_e32 v39, v39
	v_rcp_f32_e32 v40, v40
	v_rcp_f32_e32 v41, v41
	v_rcp_f32_e32 v42, v42
	v_rcp_f32_e32 v43, v43
	v_pk_mul_f32 v[28:29], v[28:29], v[36:37]
	v_pk_mul_f32 v[30:31], v[30:31], v[38:39]
	v_pk_mul_f32 v[24:25], v[24:25], v[40:41]
	v_pk_mul_f32 v[26:27], v[26:27], v[42:43]
	v_pk_mul_f32 v[20:21], v[20:21], v[28:29]
	v_pk_mul_f32 v[22:23], v[22:23], v[30:31]
	v_pk_mul_f32 v[24:25], v[16:17], v[24:25]
	v_pk_mul_f32 v[26:27], v[18:19], v[26:27]
	v_cvt_pk_bf16_f32 v16, v20, v21
	v_cvt_pk_bf16_f32 v17, v22, v23
	v_cvt_pk_bf16_f32 v18, v24, v25
	v_cvt_pk_bf16_f32 v19, v26, v27
	global_store_dwordx4 v[32:33], v[16:19], off nt
	s_andn2_b64 vcc, exec, s[6:7]
	v_mad_i64_i32 v[32:33], s[26:27], v48, s48, v[146:147]
	v_lshl_add_u64 v[16:17], v[32:33], 0, s[24:25]
	v_lshl_add_u64 v[16:17], v[16:17], 0, s[8:9]
	v_lshl_add_u64 v[16:17], v[16:17], 0, v[136:137]
	s_waitcnt lgkmcnt(0)
	v_pk_mul_f32 v[12:13], v[12:13], v[200:201] op_sel_hi:[1,0]
	v_pk_mul_f32 v[14:15], v[14:15], v[200:201] op_sel_hi:[1,0]
	v_pk_mul_f32 v[8:9], v[8:9], v[200:201] op_sel_hi:[1,0]
	v_pk_mul_f32 v[10:11], v[10:11], v[200:201] op_sel_hi:[1,0]
	v_pk_mul_f32 v[4:5], v[4:5], v[200:201] op_sel_hi:[1,0]
	v_pk_mul_f32 v[6:7], v[6:7], v[200:201] op_sel_hi:[1,0]
	v_pk_mul_f32 v[0:1], v[0:1], v[200:201] op_sel_hi:[1,0]
	v_pk_mul_f32 v[2:3], v[2:3], v[200:201] op_sel_hi:[1,0]
	v_mul_f32_e32 v18, 0xbfb8aa3b, v12
	v_mul_f32_e32 v19, 0xbfb8aa3b, v13
	v_mul_f32_e32 v20, 0xbfb8aa3b, v14
	v_mul_f32_e32 v21, 0xbfb8aa3b, v15
	v_mul_f32_e32 v22, 0xbfb8aa3b, v8
	v_mul_f32_e32 v23, 0xbfb8aa3b, v9
	v_mul_f32_e32 v24, 0xbfb8aa3b, v10
	v_mul_f32_e32 v25, 0xbfb8aa3b, v11
	v_exp_f32_e32 v18, v18
	v_exp_f32_e32 v19, v19
	v_exp_f32_e32 v20, v20
	v_exp_f32_e32 v21, v21
	v_exp_f32_e32 v22, v22
	v_exp_f32_e32 v23, v23
	v_exp_f32_e32 v24, v24
	v_exp_f32_e32 v25, v25
	v_add_f32_e32 v18, 1.0, v18
	v_add_f32_e32 v19, 1.0, v19
	v_add_f32_e32 v20, 1.0, v20
	v_add_f32_e32 v21, 1.0, v21
	v_add_f32_e32 v22, 1.0, v22
	v_add_f32_e32 v23, 1.0, v23
	v_add_f32_e32 v24, 1.0, v24
	v_add_f32_e32 v25, 1.0, v25
	v_rcp_f32_e32 v18, v18
	v_rcp_f32_e32 v19, v19
	v_rcp_f32_e32 v20, v20
	v_rcp_f32_e32 v21, v21
	v_rcp_f32_e32 v22, v22
	v_rcp_f32_e32 v23, v23
	v_rcp_f32_e32 v24, v24
	v_rcp_f32_e32 v25, v25
	v_pk_mul_f32 v[12:13], v[12:13], v[18:19]
	v_pk_mul_f32 v[14:15], v[14:15], v[20:21]
	v_pk_mul_f32 v[8:9], v[8:9], v[22:23]
	v_pk_mul_f32 v[10:11], v[10:11], v[24:25]
	v_pk_mul_f32 v[4:5], v[4:5], v[12:13]
	v_pk_mul_f32 v[6:7], v[6:7], v[14:15]
	v_pk_mul_f32 v[8:9], v[0:1], v[8:9]
	v_pk_mul_f32 v[10:11], v[2:3], v[10:11]
	v_cvt_pk_bf16_f32 v0, v4, v5
	v_cvt_pk_bf16_f32 v1, v6, v7
	v_cvt_pk_bf16_f32 v2, v8, v9
	v_cvt_pk_bf16_f32 v3, v10, v11
	s_mov_b64 s[6:7], -1
	global_store_dwordx4 v[16:17], v[0:3], off nt
	s_cbranch_vccnz .LBB0_856
	s_andn2_b64 vcc, exec, s[10:11]
	s_cbranch_vccnz .LBB0_855
	s_barrier
	s_branch .LBB0_855
